# full stack: SWA inner-loop latency edits + MLA early V reads + counted-wait relocation in the conversion loops + pipelined claims + staged rstd tables + zeroing peel + SWA prologue fix
# baseline (speedup 1.0000x reference)
.LBB0_1221:
	s_or_b32 s86, s51, s50
	s_cmp_gt_u32 s86, s57
	s_cbranch_scc1 .LBB0_1220
	v_or_b32_e32 v5, s51, v203
	s_movk_i32 s87, 0x190
	v_mad_u32_u24 v5, v5, s87, v3
	ds_read_b128 v[6:9], v5
	ds_read_b128 v[10:13], v5 offset:32
	ds_read_b128 v[14:17], v5 offset:64
	ds_read_b128 v[216:219], v5 offset:96
	ds_read_b128 v[220:223], v5 offset:128
	ds_read_b128 v[224:227], v5 offset:160
	ds_read_b128 v[228:231], v5 offset:192
	ds_read_b128 v[232:235], v5 offset:224
	s_waitcnt lgkmcnt(7)
	v_mfma_f32_32x32x16_bf16 v[82:97], v[6:9], v[98:101], 0
	ds_read_b128 v[6:9], v5 offset:256
	s_waitcnt lgkmcnt(7)
	v_mfma_f32_32x32x16_bf16 v[82:97], v[10:13], v[102:105], v[82:97]
	ds_read_b128 v[10:13], v5 offset:288
	s_waitcnt lgkmcnt(7)
	v_mfma_f32_32x32x16_bf16 v[82:97], v[14:17], v[106:109], v[82:97]
	ds_read_b128 v[14:17], v5 offset:320
	s_waitcnt lgkmcnt(7)
	v_mfma_f32_32x32x16_bf16 v[82:97], v[216:219], v[110:113], v[82:97]
	ds_read_b128 v[216:219], v5 offset:352
	s_waitcnt lgkmcnt(7)
	v_mfma_f32_32x32x16_bf16 v[82:97], v[220:223], v[114:117], v[82:97]
	s_or_b32 s87, s86, 31
	s_cmp_le_u32 s87, s24
	s_waitcnt lgkmcnt(6)
	v_mfma_f32_32x32x16_bf16 v[82:97], v[224:227], v[118:121], v[82:97]
	s_waitcnt lgkmcnt(5)
	v_mfma_f32_32x32x16_bf16 v[82:97], v[228:231], v[122:125], v[82:97]
	s_waitcnt lgkmcnt(4)
	v_mfma_f32_32x32x16_bf16 v[82:97], v[232:235], v[126:129], v[82:97]
	s_waitcnt lgkmcnt(3)
	v_mfma_f32_32x32x16_bf16 v[82:97], v[6:9], v[130:133], v[82:97]
	s_waitcnt lgkmcnt(2)
	v_mfma_f32_32x32x16_bf16 v[82:97], v[10:13], v[134:137], v[82:97]
	s_waitcnt lgkmcnt(1)
	v_mfma_f32_32x32x16_bf16 v[82:97], v[14:17], v[138:141], v[82:97]
	s_waitcnt lgkmcnt(0)
	v_mfma_f32_32x32x16_bf16 v[82:97], v[216:219], v[142:145], v[82:97]
	v_or_b32_e32 v235, s51, v205
	s_movk_i32 s98, 0x140
	v_mad_u32_u24 v235, v235, s98, v4
	ds_read_b64_tr_b16 v[238:239], v235 offset:25600
	ds_read_b64_tr_b16 v[240:241], v235 offset:28160
	ds_read_b64_tr_b16 v[242:243], v235 offset:30720
	ds_read_b64_tr_b16 v[244:245], v235 offset:33280
	ds_read_b64_tr_b16 v[246:247], v235 offset:25664
	ds_read_b64_tr_b16 v[248:249], v235 offset:28224
	s_cbranch_scc1 .LBB0_1224
	v_or_b32_e32 v5, s86, v208
	v_cmp_lt_u32_e32 vcc, v5, v213
	v_or_b32_e32 v6, 2, v5
	s_nop 7
	v_cndmask_b32_e32 v83, v212, v83, vcc
	v_cmp_le_u32_e32 vcc, v5, v213
	s_nop 1
	v_cndmask_b32_e32 v82, v212, v82, vcc
	v_cmp_le_u32_e32 vcc, v6, v213
	v_or_b32_e32 v6, 3, v5
	s_nop 0
	v_cndmask_b32_e32 v84, v212, v84, vcc
	v_cmp_le_u32_e32 vcc, v6, v213
	v_or_b32_e32 v6, 8, v5
	s_nop 0
	v_cndmask_b32_e32 v85, v212, v85, vcc
	v_cmp_le_u32_e32 vcc, v6, v213
	v_or_b32_e32 v6, 9, v5
	s_nop 0
	v_cndmask_b32_e32 v86, v212, v86, vcc
	v_cmp_le_u32_e32 vcc, v6, v213
	v_or_b32_e32 v6, 10, v5
	s_nop 0
	v_cndmask_b32_e32 v87, v212, v87, vcc
	v_cmp_le_u32_e32 vcc, v6, v213
	v_or_b32_e32 v6, 11, v5
	s_nop 0
	v_cndmask_b32_e32 v88, v212, v88, vcc
	v_cmp_le_u32_e32 vcc, v6, v213
	v_or_b32_e32 v6, 16, v5
	s_nop 0
	v_cndmask_b32_e32 v89, v212, v89, vcc
	v_cmp_le_u32_e32 vcc, v6, v213
	v_or_b32_e32 v6, 17, v5
	s_nop 0
	v_cndmask_b32_e32 v90, v212, v90, vcc
	v_cmp_le_u32_e32 vcc, v6, v213
	v_or_b32_e32 v6, 18, v5
	s_nop 0
	v_cndmask_b32_e32 v91, v212, v91, vcc
	v_cmp_le_u32_e32 vcc, v6, v213
	v_or_b32_e32 v6, 19, v5
	s_nop 0
	v_cndmask_b32_e32 v92, v212, v92, vcc
	v_cmp_le_u32_e32 vcc, v6, v213
	v_or_b32_e32 v6, 24, v5
	s_nop 0
	v_cndmask_b32_e32 v93, v212, v93, vcc
	v_cmp_le_u32_e32 vcc, v6, v213
	v_or_b32_e32 v6, 25, v5
	s_nop 0
	v_cndmask_b32_e32 v94, v212, v94, vcc
	v_cmp_le_u32_e32 vcc, v6, v213
	v_or_b32_e32 v6, 26, v5
	v_or_b32_e32 v5, 27, v5
	v_cndmask_b32_e32 v95, v212, v95, vcc
	v_cmp_le_u32_e32 vcc, v6, v213
	s_nop 1
	v_cndmask_b32_e32 v96, v212, v96, vcc
	v_cmp_le_u32_e32 vcc, v5, v213
	s_nop 1
	v_cndmask_b32_e32 v97, v212, v97, vcc

.LBB0_1226:
	v_sub_f32_e32 v6, v83, v215
	v_exp_f32_e32 v216, v6
	v_sub_f32_e32 v6, v84, v215
	v_exp_f32_e32 v217, v6
	v_sub_f32_e32 v6, v85, v215
	v_exp_f32_e32 v218, v6
	v_sub_f32_e32 v6, v86, v215
	v_exp_f32_e32 v219, v6
	v_sub_f32_e32 v6, v87, v215
	v_exp_f32_e32 v220, v6
	v_sub_f32_e32 v6, v88, v215
	v_exp_f32_e32 v221, v6
	v_sub_f32_e32 v6, v89, v215
	v_exp_f32_e32 v222, v6
	v_sub_f32_e32 v6, v90, v215
	v_exp_f32_e32 v90, v6
	v_sub_f32_e32 v6, v91, v215
	v_exp_f32_e32 v91, v6
	v_sub_f32_e32 v6, v92, v215
	v_exp_f32_e32 v92, v6
	v_sub_f32_e32 v6, v93, v215
	v_exp_f32_e32 v93, v6
	v_sub_f32_e32 v6, v94, v215
	v_exp_f32_e32 v94, v6
	v_sub_f32_e32 v6, v95, v215
	v_exp_f32_e32 v95, v6
	v_or_b32_e32 v6, s51, v205
	s_movk_i32 s51, 0x140
	v_sub_f32_e32 v5, v82, v215
	v_mad_u32_u24 v88, v6, s51, v4
	v_exp_f32_e32 v5, v5
	v_sub_f32_e32 v10, v96, v215
	v_exp_f32_e32 v96, v10
	v_cvt_pk_bf16_f32 v10, v5, v216
	v_cvt_pk_bf16_f32 v11, v217, v218
	v_cvt_pk_bf16_f32 v12, v219, v220
	v_cvt_pk_bf16_f32 v13, v221, v222
	s_waitcnt lgkmcnt(0)
	v_mfma_f32_32x32x16_bf16 v[66:81], v[238:241], v[10:13], v[66:81]
	v_sub_f32_e32 v6, v97, v215
	v_exp_f32_e32 v97, v6
	v_cvt_pk_bf16_f32 v6, v90, v91
	v_cvt_pk_bf16_f32 v7, v92, v93
	v_cvt_pk_bf16_f32 v8, v94, v95
	v_cvt_pk_bf16_f32 v9, v96, v97
	v_add_f32_e32 v5, 0, v5
	v_add_f32_e32 v5, v216, v5
	s_waitcnt lgkmcnt(1)
	v_mfma_f32_32x32x16_bf16 v[66:81], v[242:245], v[6:9], v[66:81]
	ds_read_b64_tr_b16 v[14:15], v88 offset:30784
	v_add_f32_e32 v5, v217, v5
	v_add_f32_e32 v5, v218, v5
	v_add_f32_e32 v5, v219, v5
	v_add_f32_e32 v5, v220, v5
	v_add_f32_e32 v5, v221, v5
	v_add_f32_e32 v5, v222, v5
	s_waitcnt lgkmcnt(1)
	v_mfma_f32_32x32x16_bf16 v[50:65], v[246:249], v[10:13], v[50:65]
	ds_read_b64_tr_b16 v[16:17], v88 offset:33344
	ds_read_b64_tr_b16 v[82:83], v88 offset:25728
	v_add_f32_e32 v5, v90, v5
	v_add_f32_e32 v5, v91, v5
	v_add_f32_e32 v5, v92, v5
	v_add_f32_e32 v5, v93, v5
	v_add_f32_e32 v5, v94, v5
	v_add_f32_e32 v5, v95, v5
	s_waitcnt lgkmcnt(1)
	v_mfma_f32_32x32x16_bf16 v[50:65], v[14:17], v[6:9], v[50:65]
	ds_read_b64_tr_b16 v[84:85], v88 offset:28288
	ds_read_b64_tr_b16 v[14:15], v88 offset:30848
	ds_read_b64_tr_b16 v[16:17], v88 offset:33408
	v_add_f32_e32 v5, v96, v5
	v_add_f32_e32 v5, v97, v5
	s_xor_b64 s[86:87], s[6:7], -1
	v_add_f32_e32 v214, v214, v5
	s_waitcnt lgkmcnt(2)
	v_mfma_f32_32x32x16_bf16 v[34:49], v[82:85], v[10:13], v[34:49]
	ds_read_b64_tr_b16 v[82:83], v88 offset:25792
	ds_read_b64_tr_b16 v[84:85], v88 offset:28352
	ds_read_b64_tr_b16 v[86:87], v88 offset:30912
	ds_read_b64_tr_b16 v[88:89], v88 offset:33472
	s_waitcnt lgkmcnt(2)
	v_mfma_f32_32x32x16_bf16 v[18:33], v[82:85], v[10:13], v[18:33]
	v_mfma_f32_32x32x16_bf16 v[34:49], v[14:17], v[6:9], v[34:49]
	s_waitcnt lgkmcnt(0)
	v_mfma_f32_32x32x16_bf16 v[18:33], v[86:89], v[6:9], v[18:33]
	s_mov_b32 s51, 32
	s_mov_b64 s[6:7], 0
	s_and_b64 vcc, exec, s[86:87]
	s_cbranch_vccz .LBB0_1221
